# MLP-up: 1/rms of the workgroup's 256 rows computed once per phase into a 1 KB LDS table (same sum tree, same sqrt/div sequence); tile epilogues read it instead of recomputing per row group
# speedup vs baseline: 1.0116x; 1.0048x over previous
;     __device__ __forceinline__ void operator()(const f32x4 (&acc)[2][2][4][2], const Unit& u, int wr, int wc, int fr, int fq) const {
;     ...
;             for (int m = 0; m < 4; ++m) { const size_t row = (size_t)(row0 + ai * HALF + m * 16);
;                 const f32x4* sp = (const f32x4*)(SS + row * 32) + 2 * fq; float s;
;                 { const f32x4 t0 = sp[0], t1 = sp[1]; s = ((t0[0] + t0[1]) + (t0[2] + t0[3])) + ((t1[0] + t1[1]) + (t1[2] + t1[3])); }
;                 s += __shfl_xor(s, 16); s += __shfl_xor(s, 32);
;                 const float rstd = 1.0f / sqrtf(s * (1.0f / DM) + NORM_EPS);
.LBB0_66:
	v_bfe_u32 v18, v16, 4, 2
	v_and_b32_e32 v17, 15, v16
	v_lshlrev_b32_e32 v19, 4, v18
	v_lshlrev_b32_e32 v16, 2, v16
	v_lshl_or_b32 v1, s19, 6, v17
	v_lshl_or_b32 v17, v17, 6, v19
	s_lshl_b32 s19, s19, 13
	v_and_b32_e32 v16, 32, v16
	s_lshl_b32 s5, s5, 5
	v_bitop3_b32 v19, v17, s19, v16 bitop3:0xde
	s_and_b32 s19, s5, 0x60
	s_lshl_b32 s5, s19, 7
	s_add_i32 m0, s62, 0x18000
	v_lshl_add_u64 v[8:9], v[8:9], 0, s[68:69]
	v_bitop3_b32 v143, v17, s5, v16 bitop3:0xde
	s_waitcnt vmcnt(2)
	s_barrier
	global_load_lds_dwordx4 v[8:9], off
	v_lshl_add_u64 v[6:7], v[6:7], 0, s[68:69]
	s_add_i32 m0, s62, 0x1a000
	s_add_i32 s5, s62, 0x8000
	s_add_i32 s57, s62, 0xa000
	global_load_lds_dwordx4 v[6:7], off
	v_lshl_add_u64 v[2:3], v[2:3], 0, s[68:69]
	s_mov_b32 m0, s5
	s_add_u32 s36, s58, 0x80080
	global_load_lds_dwordx4 v[2:3], off
	v_lshl_add_u64 v[2:3], v[4:5], 0, s[68:69]
	s_mov_b32 m0, s57
	s_addc_u32 s37, s59, 0
	global_load_lds_dwordx4 v[2:3], off
	s_add_i32 m0, s62, 0x1c000
	v_lshl_add_u64 v[2:3], s[36:37], 0, v[148:149]
	global_load_lds_dwordx4 v[2:3], off
	v_lshl_add_u64 v[2:3], s[36:37], 0, v[144:145]
	s_add_i32 m0, s62, 0x1e000
	s_cmpk_lt_u32 s18, 0x100
	global_load_lds_dwordx4 v[2:3], off
	v_lshlrev_b32_e32 v2, 5, v18
	v_mov_b32_e32 v3, v0
	v_lshl_add_u64 v[152:153], s[10:11], 0, v[2:3]
	v_lshlrev_b32_e32 v2, 15, v14
	v_and_b32_e32 v2, 0xffff0000, v2
	v_lshl_add_u32 v2, v13, 12, v2
	v_and_b32_e32 v3, 1, v14
	v_lshl_or_b32 v2, v3, 6, v2
	v_lshl_add_u32 v154, v15, 1, v2
	v_lshlrev_b32_e32 v2, 15, v10
	v_and_b32_e32 v2, 0xffff0000, v2
	s_waitcnt vmcnt(6)
	v_lshl_add_u32 v2, v11, 12, v2
	v_and_b32_e32 v3, 1, v10
	v_lshl_or_b32 v160, v18, 3, s19
	v_lshl_or_b32 v2, v3, 6, v2
	v_readlane_b32 s18, v253, 54
	s_cselect_b64 s[42:43], -1, 0
	v_mov_b32_e32 v155, v0
	v_lshl_add_u32 v156, v12, 1, v2
	v_mov_b32_e32 v157, v0
	s_mov_b32 s30, 0
	v_add_u32_e32 v161, 0, v19
	v_readlane_b32 s28, v253, 16
	s_mov_b32 s34, s18
	s_barrier
	v_lshrrev_b32_e32 v20, 1, v188
	v_and_b32_e32 v21, 1, v188
	v_lshl_add_u32 v22, s34, 8, v20
	v_lshlrev_b32_e32 v22, 7, v22
	v_lshl_or_b32 v22, v21, 6, v22
	v_mov_b32_e32 v23, 0
	v_lshl_add_u64 v[22:23], s[10:11], 0, v[22:23]
	global_load_dwordx4 v[24:27], v[22:23], off
	global_load_dwordx4 v[28:31], v[22:23], off offset:16
	global_load_dwordx4 v[32:35], v[22:23], off offset:32
	global_load_dwordx4 v[36:39], v[22:23], off offset:48
	s_waitcnt vmcnt(0)
	v_add_f32_e32 v24, v24, v25
	v_add_f32_e32 v26, v26, v27
	v_add_f32_e32 v28, v28, v29
	v_add_f32_e32 v30, v30, v31
	v_add_f32_e32 v24, v24, v26
	v_add_f32_e32 v28, v28, v30
	v_add_f32_e32 v24, v24, v28
	v_add_f32_e32 v32, v32, v33
	v_add_f32_e32 v34, v34, v35
	v_add_f32_e32 v36, v36, v37
	v_add_f32_e32 v38, v38, v39
	v_add_f32_e32 v32, v32, v34
	v_add_f32_e32 v36, v36, v38
	v_add_f32_e32 v32, v32, v36
	v_add_f32_e32 v40, v24, v32
	s_nop 1
	v_add_f32_dpp v40, v40, v40 quad_perm:[1,0,3,2] row_mask:0xf bank_mask:0xf
	v_fmamk_f32 v40, v40, 0x3a000000, v190
	v_cmp_gt_f32_e32 vcc, s72, v40
	v_mul_f32_e32 v41, 0x4f800000, v40
	s_nop 0
	v_cndmask_b32_e32 v40, v40, v41, vcc
	v_sqrt_f32_e32 v41, v40
	s_nop 0
	v_add_u32_e32 v42, -1, v41
	v_fma_f32 v43, -v42, v41, v40
	v_cmp_ge_f32_e64 s[18:19], 0, v43
	v_add_u32_e32 v43, 1, v41
	s_nop 0
	v_cndmask_b32_e64 v42, v41, v42, s[18:19]
	v_fma_f32 v41, -v43, v41, v40
	v_cmp_lt_f32_e64 s[18:19], 0, v41
	s_nop 1
	v_cndmask_b32_e64 v41, v42, v43, s[18:19]
	v_mul_f32_e32 v42, 0x37800000, v41
	v_cndmask_b32_e32 v41, v41, v42, vcc
	v_cmp_class_f32_e32 vcc, v40, v191
	s_nop 1
	v_cndmask_b32_e32 v40, v41, v40, vcc
	v_div_scale_f32 v41, s[18:19], v40, v40, 1.0
	v_rcp_f32_e32 v42, v41
	s_nop 0
	v_fma_f32 v43, -v41, v42, 1.0
	v_fmac_f32_e32 v42, v43, v42
	v_div_scale_f32 v43, vcc, 1.0, v40, 1.0
	v_mul_f32_e32 v44, v43, v42
	v_fma_f32 v45, -v41, v44, v43
	v_fmac_f32_e32 v44, v45, v42
	v_fma_f32 v41, -v41, v44, v43
	v_div_fmas_f32 v41, v41, v42, v44
	v_div_fixup_f32 v40, v41, v40, 1.0
	v_lshlrev_b32_e32 v46, 2, v20
	v_add_u32_e32 v46, 0x22c00, v46
	ds_write_b32 v46, v40
	s_waitcnt lgkmcnt(0)
	s_barrier
	v_readlane_b32 s19, v253, 55
	s_mov_b32 s32, 0
	s_branch .LBB0_69

; __device__ __forceinline__ unsigned cvt_pk_bf16(float lo, float hi) { const f32x2c_t v = {lo, hi}; const bf16x2c_t b = __builtin_convertvector(v, bf16x2c_t); return __builtin_bit_cast(unsigned, b); }
;     __device__ __forceinline__ void operator()(const f32x4 (&acc)[2][2][4][2], const Unit& u, int wr, int wc, int fr, int fq) const {
;     ...
;             for (int m = 0; m < 4; ++m) { const size_t row = (size_t)(row0 + ai * HALF + m * 16);
;                 const f32x4* sp = (const f32x4*)(SS + row * 32) + 2 * fq; float s;
;                 { const f32x4 t0 = sp[0], t1 = sp[1]; s = ((t0[0] + t0[1]) + (t0[2] + t0[3])) + ((t1[0] + t1[1]) + (t1[2] + t1[3])); }
;                 s += __shfl_xor(s, 16); s += __shfl_xor(s, 32);
;                 const float rstd = 1.0f / sqrtf(s * (1.0f / DM) + NORM_EPS);
; #pragma unroll
;                 for (int bj = 0; bj < 2; ++bj) { f32x4 v0 = acc[ai][bj][m][0] * rstd, v1 = acc[ai][bj][m][1] * rstd;
; #pragma unroll
;                     for (int e = 0; e < 4; ++e) { const float a = fmaxf(v0[e], 0.f), b = fmaxf(v1[e], 0.f); v0[e] = a * a; v1[e] = b * b; }
;                     u32x4 w; w.x = cvt_pk_bf16(v0[0], v0[1]); w.y = cvt_pk_bf16(v0[2], v0[3]); w.z = cvt_pk_bf16(v1[0], v1[1]); w.w = cvt_pk_bf16(v1[2], v1[3]);
;                     *(u32x4*)(H + row * DFF + col0 + bj * HALF) = w; } }
.LBB0_79:
	v_lshlrev_b32_e32 v220, 2, v1
	v_add_u32_e32 v220, 0x22c00, v220
	ds_read_b32 v204, v220 offset:0
	ds_read_b32 v206, v220 offset:64
	ds_read_b32 v208, v220 offset:128
	ds_read_b32 v210, v220 offset:192
	ds_read_b32 v212, v220 offset:512
	ds_read_b32 v214, v220 offset:576
	ds_read_b32 v216, v220 offset:640
	ds_read_b32 v218, v220 offset:704
	s_waitcnt lgkmcnt(0)
	v_xor_b32_e32 v159, 16, v192
	v_add_u32_e32 v163, 64, v193
	v_cmp_lt_i32_e32 vcc, v159, v163
	v_lshl_add_u32 v158, s34, 8, v1
	v_lshl_or_b32 v172, s28, 8, v160
	v_cndmask_b32_e32 v159, v192, v159, vcc
	v_lshlrev_b32_e32 v162, 2, v159
	v_xor_b32_e32 v159, 32, v192
	v_cmp_lt_i32_e32 vcc, v159, v163
	v_ashrrev_i32_e32 v173, 31, v172
	s_nop 0
	v_cndmask_b32_e32 v159, v192, v159, vcc
	v_lshlrev_b32_e32 v163, 2, v159
	v_ashrrev_i32_e32 v159, 31, v158
	v_lshlrev_b64 v[164:165], 7, v[158:159]
	v_lshl_add_u64 v[168:169], v[152:153], 0, v[164:165]
	v_pk_mul_f32 v[128:129], v[128:129], v[204:205] op_sel_hi:[1,0]
	v_pk_mul_f32 v[126:127], v[126:127], v[204:205] op_sel_hi:[1,0]
	v_pk_mul_f32 v[122:123], v[122:123], v[204:205] op_sel_hi:[1,0]
	v_pk_mul_f32 v[124:125], v[124:125], v[204:205] op_sel_hi:[1,0]
	v_max_f32_e32 v126, 0, v126
	v_max_f32_e32 v122, 0, v122
	v_max_f32_e32 v127, 0, v127
	v_max_f32_e32 v123, 0, v123
	v_max_f32_e32 v128, 0, v128
	v_max_f32_e32 v129, 0, v129
	v_lshlrev_b64 v[166:167], 14, v[158:159]
	v_pk_mul_f32 v[126:127], v[126:127], v[126:127]
	v_pk_mul_f32 v[122:123], v[122:123], v[122:123]
	v_max_f32_e32 v124, 0, v124
	v_max_f32_e32 v125, 0, v125
	v_pk_mul_f32 v[128:129], v[128:129], v[128:129]
	v_pk_mul_f32 v[168:169], v[124:125], v[124:125]
	v_cvt_pk_bf16_f32 v124, v126, v127
	v_cvt_pk_bf16_f32 v125, v128, v129
	v_cvt_pk_bf16_f32 v126, v122, v123
	v_lshl_add_u64 v[128:129], s[92:93], 0, v[166:167]
	v_lshlrev_b64 v[122:123], 1, v[172:173]
	v_pk_mul_f32 v[114:115], v[114:115], v[204:205] op_sel_hi:[1,0]
	v_cvt_pk_bf16_f32 v127, v168, v169
	v_lshl_add_u64 v[128:129], v[128:129], 0, v[122:123]
	v_pk_mul_f32 v[120:121], v[120:121], v[204:205] op_sel_hi:[1,0]
	v_pk_mul_f32 v[118:119], v[118:119], v[204:205] op_sel_hi:[1,0]
	v_pk_mul_f32 v[116:117], v[116:117], v[204:205] op_sel_hi:[1,0]
	v_max_f32_e32 v114, 0, v114
	v_max_f32_e32 v115, 0, v115
	global_store_dwordx4 v[128:129], v[124:127], off
	v_max_f32_e32 v118, 0, v118
	v_max_f32_e32 v119, 0, v119
	v_pk_mul_f32 v[124:125], v[114:115], v[114:115]
	v_max_f32_e32 v114, 0, v120
	v_max_f32_e32 v116, 0, v116
	v_max_f32_e32 v115, 0, v121
	v_max_f32_e32 v117, 0, v117
	v_pk_mul_f32 v[118:119], v[118:119], v[118:119]
	v_pk_mul_f32 v[120:121], v[114:115], v[114:115]
	v_pk_mul_f32 v[126:127], v[116:117], v[116:117]
	v_cvt_pk_bf16_f32 v114, v118, v119
	v_cvt_pk_bf16_f32 v115, v120, v121
	v_cvt_pk_bf16_f32 v116, v124, v125
	v_cvt_pk_bf16_f32 v117, v126, v127
	global_store_dwordx4 v[128:129], v[114:117], off offset:256
	s_nop 1
	v_or_b32_e32 v114, 16, v158
	v_ashrrev_i32_e32 v115, 31, v114
	v_lshlrev_b64 v[116:117], 7, v[114:115]
	v_lshl_add_u64 v[120:121], v[152:153], 0, v[116:117]
	v_lshlrev_b64 v[114:115], 14, v[114:115]
	v_pk_mul_f32 v[110:111], v[110:111], v[206:207] op_sel_hi:[1,0]
	v_pk_mul_f32 v[106:107], v[106:107], v[206:207] op_sel_hi:[1,0]
	v_pk_mul_f32 v[112:113], v[112:113], v[206:207] op_sel_hi:[1,0]
	v_pk_mul_f32 v[108:109], v[108:109], v[206:207] op_sel_hi:[1,0]
	v_max_f32_e32 v110, 0, v110
	v_max_f32_e32 v106, 0, v106
	v_max_f32_e32 v111, 0, v111
	v_max_f32_e32 v107, 0, v107
	v_pk_mul_f32 v[110:111], v[110:111], v[110:111]
	v_pk_mul_f32 v[118:119], v[106:107], v[106:107]
	v_max_f32_e32 v106, 0, v112
	v_max_f32_e32 v108, 0, v108
	v_max_f32_e32 v107, 0, v113
	v_max_f32_e32 v109, 0, v109
	v_pk_mul_f32 v[112:113], v[106:107], v[106:107]
	v_pk_mul_f32 v[120:121], v[108:109], v[108:109]
	v_cvt_pk_bf16_f32 v106, v110, v111
	v_lshl_add_u64 v[110:111], s[92:93], 0, v[114:115]
	v_pk_mul_f32 v[98:99], v[98:99], v[206:207] op_sel_hi:[1,0]
	v_cvt_pk_bf16_f32 v107, v112, v113
	v_cvt_pk_bf16_f32 v108, v118, v119
	v_cvt_pk_bf16_f32 v109, v120, v121
	v_lshl_add_u64 v[110:111], v[110:111], 0, v[122:123]
	v_pk_mul_f32 v[104:105], v[104:105], v[206:207] op_sel_hi:[1,0]
	v_pk_mul_f32 v[102:103], v[102:103], v[206:207] op_sel_hi:[1,0]
	v_pk_mul_f32 v[100:101], v[100:101], v[206:207] op_sel_hi:[1,0]
	v_max_f32_e32 v98, 0, v98
	v_max_f32_e32 v99, 0, v99
	global_store_dwordx4 v[110:111], v[106:109], off
	v_max_f32_e32 v102, 0, v102
	v_max_f32_e32 v103, 0, v103
	v_pk_mul_f32 v[106:107], v[98:99], v[98:99]
	v_max_f32_e32 v98, 0, v104
	v_max_f32_e32 v100, 0, v100
	v_max_f32_e32 v99, 0, v105
	v_max_f32_e32 v101, 0, v101
	v_pk_mul_f32 v[102:103], v[102:103], v[102:103]
	v_pk_mul_f32 v[104:105], v[98:99], v[98:99]
	v_pk_mul_f32 v[108:109], v[100:101], v[100:101]
	v_cvt_pk_bf16_f32 v98, v102, v103
	v_cvt_pk_bf16_f32 v99, v104, v105
	v_cvt_pk_bf16_f32 v100, v106, v107
	v_cvt_pk_bf16_f32 v101, v108, v109
	global_store_dwordx4 v[110:111], v[98:101], off offset:256
	s_nop 1
	v_or_b32_e32 v98, 32, v158
	v_ashrrev_i32_e32 v99, 31, v98
	v_lshlrev_b64 v[100:101], 7, v[98:99]
	v_lshl_add_u64 v[100:101], v[152:153], 0, v[100:101]
	v_lshlrev_b64 v[98:99], 14, v[98:99]
	v_pk_mul_f32 v[94:95], v[94:95], v[208:209] op_sel_hi:[1,0]
	v_pk_mul_f32 v[90:91], v[90:91], v[208:209] op_sel_hi:[1,0]
	v_pk_mul_f32 v[96:97], v[96:97], v[208:209] op_sel_hi:[1,0]
	v_pk_mul_f32 v[92:93], v[92:93], v[208:209] op_sel_hi:[1,0]
	v_max_f32_e32 v94, 0, v94
	v_max_f32_e32 v90, 0, v90
	v_max_f32_e32 v95, 0, v95
	v_max_f32_e32 v91, 0, v91
	v_pk_mul_f32 v[94:95], v[94:95], v[94:95]
	v_pk_mul_f32 v[102:103], v[90:91], v[90:91]
	v_max_f32_e32 v90, 0, v96
	v_max_f32_e32 v92, 0, v92
; __device__ __forceinline__ unsigned cvt_pk_bf16(float lo, float hi) { const f32x2c_t v = {lo, hi}; const bf16x2c_t b = __builtin_convertvector(v, bf16x2c_t); return __builtin_bit_cast(unsigned, b); }
;     __device__ __forceinline__ void operator()(const f32x4 (&acc)[2][2][4][2], const Unit& u, int wr, int wc, int fr, int fq) const {
;     ...
;             for (int m = 0; m < 4; ++m) { const size_t row = (size_t)(row0 + ai * HALF + m * 16);
;                 const f32x4* sp = (const f32x4*)(SS + row * 32) + 2 * fq; float s;
;                 { const f32x4 t0 = sp[0], t1 = sp[1]; s = ((t0[0] + t0[1]) + (t0[2] + t0[3])) + ((t1[0] + t1[1]) + (t1[2] + t1[3])); }
;                 s += __shfl_xor(s, 16); s += __shfl_xor(s, 32);
;                 const float rstd = 1.0f / sqrtf(s * (1.0f / DM) + NORM_EPS);
; #pragma unroll
;                 for (int bj = 0; bj < 2; ++bj) { f32x4 v0 = acc[ai][bj][m][0] * rstd, v1 = acc[ai][bj][m][1] * rstd;
; #pragma unroll
;                     for (int e = 0; e < 4; ++e) { const float a = fmaxf(v0[e], 0.f), b = fmaxf(v1[e], 0.f); v0[e] = a * a; v1[e] = b * b; }
;                     u32x4 w; w.x = cvt_pk_bf16(v0[0], v0[1]); w.y = cvt_pk_bf16(v0[2], v0[3]); w.z = cvt_pk_bf16(v1[0], v1[1]); w.w = cvt_pk_bf16(v1[2], v1[3]);
;                     *(u32x4*)(H + row * DFF + col0 + bj * HALF) = w; } }
	v_max_f32_e32 v91, 0, v97
	v_max_f32_e32 v93, 0, v93
	v_pk_mul_f32 v[96:97], v[90:91], v[90:91]
	v_pk_mul_f32 v[104:105], v[92:93], v[92:93]
	v_cvt_pk_bf16_f32 v90, v94, v95
	v_lshl_add_u64 v[94:95], s[92:93], 0, v[98:99]
	v_pk_mul_f32 v[82:83], v[82:83], v[208:209] op_sel_hi:[1,0]
	v_cvt_pk_bf16_f32 v91, v96, v97
	v_cvt_pk_bf16_f32 v92, v102, v103
	v_cvt_pk_bf16_f32 v93, v104, v105
	v_lshl_add_u64 v[94:95], v[94:95], 0, v[122:123]
	v_pk_mul_f32 v[88:89], v[88:89], v[208:209] op_sel_hi:[1,0]
	v_pk_mul_f32 v[86:87], v[86:87], v[208:209] op_sel_hi:[1,0]
	v_pk_mul_f32 v[84:85], v[84:85], v[208:209] op_sel_hi:[1,0]
	v_max_f32_e32 v82, 0, v82
	v_max_f32_e32 v83, 0, v83
	global_store_dwordx4 v[94:95], v[90:93], off
	v_max_f32_e32 v86, 0, v86
	v_max_f32_e32 v87, 0, v87
	v_pk_mul_f32 v[90:91], v[82:83], v[82:83]
	v_max_f32_e32 v82, 0, v88
	v_max_f32_e32 v84, 0, v84
	v_max_f32_e32 v83, 0, v89
	v_max_f32_e32 v85, 0, v85
	v_pk_mul_f32 v[86:87], v[86:87], v[86:87]
	v_pk_mul_f32 v[88:89], v[82:83], v[82:83]
	v_pk_mul_f32 v[92:93], v[84:85], v[84:85]
	v_cvt_pk_bf16_f32 v82, v86, v87
	v_cvt_pk_bf16_f32 v83, v88, v89
	v_cvt_pk_bf16_f32 v84, v90, v91
	v_cvt_pk_bf16_f32 v85, v92, v93
	global_store_dwordx4 v[94:95], v[82:85], off offset:256
	s_nop 1
	v_or_b32_e32 v82, 48, v158
	v_ashrrev_i32_e32 v83, 31, v82
	v_lshlrev_b64 v[84:85], 7, v[82:83]
	v_lshl_add_u64 v[84:85], v[152:153], 0, v[84:85]
	v_lshlrev_b64 v[82:83], 14, v[82:83]
	v_pk_mul_f32 v[78:79], v[78:79], v[210:211] op_sel_hi:[1,0]
	v_pk_mul_f32 v[74:75], v[74:75], v[210:211] op_sel_hi:[1,0]
	v_pk_mul_f32 v[80:81], v[80:81], v[210:211] op_sel_hi:[1,0]
	v_pk_mul_f32 v[76:77], v[76:77], v[210:211] op_sel_hi:[1,0]
	v_max_f32_e32 v78, 0, v78
	v_max_f32_e32 v74, 0, v74
	v_max_f32_e32 v79, 0, v79
	v_max_f32_e32 v75, 0, v75
	v_pk_mul_f32 v[78:79], v[78:79], v[78:79]
	v_pk_mul_f32 v[86:87], v[74:75], v[74:75]
	v_max_f32_e32 v74, 0, v80
	v_max_f32_e32 v76, 0, v76
	v_max_f32_e32 v75, 0, v81
	v_max_f32_e32 v77, 0, v77
	v_pk_mul_f32 v[80:81], v[74:75], v[74:75]
	v_pk_mul_f32 v[88:89], v[76:77], v[76:77]
	v_cvt_pk_bf16_f32 v74, v78, v79
	v_lshl_add_u64 v[78:79], s[92:93], 0, v[82:83]
	v_pk_mul_f32 v[66:67], v[66:67], v[210:211] op_sel_hi:[1,0]
	v_cvt_pk_bf16_f32 v75, v80, v81
	v_cvt_pk_bf16_f32 v76, v86, v87
	v_cvt_pk_bf16_f32 v77, v88, v89
	v_lshl_add_u64 v[78:79], v[78:79], 0, v[122:123]
	v_pk_mul_f32 v[72:73], v[72:73], v[210:211] op_sel_hi:[1,0]
	v_pk_mul_f32 v[70:71], v[70:71], v[210:211] op_sel_hi:[1,0]
	v_pk_mul_f32 v[68:69], v[68:69], v[210:211] op_sel_hi:[1,0]
	v_max_f32_e32 v66, 0, v66
	v_max_f32_e32 v67, 0, v67
	global_store_dwordx4 v[78:79], v[74:77], off
	v_max_f32_e32 v70, 0, v70
	v_max_f32_e32 v71, 0, v71
	v_pk_mul_f32 v[74:75], v[66:67], v[66:67]
	v_max_f32_e32 v66, 0, v72
	v_max_f32_e32 v68, 0, v68
	v_max_f32_e32 v67, 0, v73
	v_max_f32_e32 v69, 0, v69
	v_pk_mul_f32 v[70:71], v[70:71], v[70:71]
	v_pk_mul_f32 v[72:73], v[66:67], v[66:67]
	v_pk_mul_f32 v[76:77], v[68:69], v[68:69]
	v_cvt_pk_bf16_f32 v66, v70, v71
	v_cvt_pk_bf16_f32 v67, v72, v73
	v_cvt_pk_bf16_f32 v68, v74, v75
	v_cvt_pk_bf16_f32 v69, v76, v77
	global_store_dwordx4 v[78:79], v[66:69], off offset:256
	s_nop 1
	v_add_u32_e32 v66, 0x80, v158
	v_ashrrev_i32_e32 v67, 31, v66
	v_lshlrev_b64 v[68:69], 7, v[66:67]
	v_lshl_add_u64 v[68:69], v[152:153], 0, v[68:69]
	v_lshlrev_b64 v[66:67], 14, v[66:67]
	v_pk_mul_f32 v[62:63], v[62:63], v[212:213] op_sel_hi:[1,0]
	v_pk_mul_f32 v[58:59], v[58:59], v[212:213] op_sel_hi:[1,0]
	v_pk_mul_f32 v[64:65], v[64:65], v[212:213] op_sel_hi:[1,0]
	v_pk_mul_f32 v[60:61], v[60:61], v[212:213] op_sel_hi:[1,0]
	v_max_f32_e32 v62, 0, v62
	v_max_f32_e32 v58, 0, v58
	v_max_f32_e32 v63, 0, v63
	v_max_f32_e32 v59, 0, v59
	v_pk_mul_f32 v[62:63], v[62:63], v[62:63]
	v_pk_mul_f32 v[70:71], v[58:59], v[58:59]
	v_max_f32_e32 v58, 0, v64
	v_max_f32_e32 v60, 0, v60
	v_max_f32_e32 v59, 0, v65
	v_max_f32_e32 v61, 0, v61
	v_pk_mul_f32 v[64:65], v[58:59], v[58:59]
	v_pk_mul_f32 v[72:73], v[60:61], v[60:61]
	v_cvt_pk_bf16_f32 v58, v62, v63
	v_lshl_add_u64 v[62:63], s[92:93], 0, v[66:67]
	v_pk_mul_f32 v[50:51], v[50:51], v[212:213] op_sel_hi:[1,0]
	v_cvt_pk_bf16_f32 v59, v64, v65
	v_cvt_pk_bf16_f32 v60, v70, v71
	v_cvt_pk_bf16_f32 v61, v72, v73
	v_lshl_add_u64 v[62:63], v[62:63], 0, v[122:123]
	v_pk_mul_f32 v[56:57], v[56:57], v[212:213] op_sel_hi:[1,0]
	v_pk_mul_f32 v[54:55], v[54:55], v[212:213] op_sel_hi:[1,0]
	v_pk_mul_f32 v[52:53], v[52:53], v[212:213] op_sel_hi:[1,0]
	v_max_f32_e32 v50, 0, v50
	v_max_f32_e32 v51, 0, v51
	global_store_dwordx4 v[62:63], v[58:61], off
	v_max_f32_e32 v54, 0, v54
	v_max_f32_e32 v55, 0, v55
	v_pk_mul_f32 v[58:59], v[50:51], v[50:51]
	v_max_f32_e32 v50, 0, v56
	v_max_f32_e32 v52, 0, v52
	v_max_f32_e32 v51, 0, v57
	v_max_f32_e32 v53, 0, v53
	v_pk_mul_f32 v[54:55], v[54:55], v[54:55]
	v_pk_mul_f32 v[56:57], v[50:51], v[50:51]
	v_pk_mul_f32 v[60:61], v[52:53], v[52:53]
	v_cvt_pk_bf16_f32 v50, v54, v55
	v_cvt_pk_bf16_f32 v51, v56, v57
	v_cvt_pk_bf16_f32 v52, v58, v59
	v_cvt_pk_bf16_f32 v53, v60, v61
	global_store_dwordx4 v[62:63], v[50:53], off offset:256
	s_nop 1
	v_add_u32_e32 v50, 0x90, v158
	v_ashrrev_i32_e32 v51, 31, v50
	v_lshlrev_b64 v[52:53], 7, v[50:51]
	v_lshl_add_u64 v[52:53], v[152:153], 0, v[52:53]
	v_lshlrev_b64 v[50:51], 14, v[50:51]
	v_pk_mul_f32 v[46:47], v[46:47], v[214:215] op_sel_hi:[1,0]
	v_pk_mul_f32 v[42:43], v[42:43], v[214:215] op_sel_hi:[1,0]
	v_pk_mul_f32 v[48:49], v[48:49], v[214:215] op_sel_hi:[1,0]
; __device__ __forceinline__ unsigned cvt_pk_bf16(float lo, float hi) { const f32x2c_t v = {lo, hi}; const bf16x2c_t b = __builtin_convertvector(v, bf16x2c_t); return __builtin_bit_cast(unsigned, b); }
;     __device__ __forceinline__ void operator()(const f32x4 (&acc)[2][2][4][2], const Unit& u, int wr, int wc, int fr, int fq) const {
;     ...
;             for (int m = 0; m < 4; ++m) { const size_t row = (size_t)(row0 + ai * HALF + m * 16);
;                 const f32x4* sp = (const f32x4*)(SS + row * 32) + 2 * fq; float s;
;                 { const f32x4 t0 = sp[0], t1 = sp[1]; s = ((t0[0] + t0[1]) + (t0[2] + t0[3])) + ((t1[0] + t1[1]) + (t1[2] + t1[3])); }
;                 s += __shfl_xor(s, 16); s += __shfl_xor(s, 32);
;                 const float rstd = 1.0f / sqrtf(s * (1.0f / DM) + NORM_EPS);
; #pragma unroll
;                 for (int bj = 0; bj < 2; ++bj) { f32x4 v0 = acc[ai][bj][m][0] * rstd, v1 = acc[ai][bj][m][1] * rstd;
; #pragma unroll
;                     for (int e = 0; e < 4; ++e) { const float a = fmaxf(v0[e], 0.f), b = fmaxf(v1[e], 0.f); v0[e] = a * a; v1[e] = b * b; }
;                     u32x4 w; w.x = cvt_pk_bf16(v0[0], v0[1]); w.y = cvt_pk_bf16(v0[2], v0[3]); w.z = cvt_pk_bf16(v1[0], v1[1]); w.w = cvt_pk_bf16(v1[2], v1[3]);
;                     *(u32x4*)(H + row * DFF + col0 + bj * HALF) = w; } }
	v_pk_mul_f32 v[44:45], v[44:45], v[214:215] op_sel_hi:[1,0]
	v_max_f32_e32 v46, 0, v46
	v_max_f32_e32 v42, 0, v42
	v_max_f32_e32 v47, 0, v47
	v_max_f32_e32 v43, 0, v43
	v_pk_mul_f32 v[46:47], v[46:47], v[46:47]
	v_pk_mul_f32 v[54:55], v[42:43], v[42:43]
	v_max_f32_e32 v42, 0, v48
	v_max_f32_e32 v44, 0, v44
	v_max_f32_e32 v43, 0, v49
	v_max_f32_e32 v45, 0, v45
	v_pk_mul_f32 v[48:49], v[42:43], v[42:43]
	v_pk_mul_f32 v[56:57], v[44:45], v[44:45]
	v_cvt_pk_bf16_f32 v42, v46, v47
	v_lshl_add_u64 v[46:47], s[92:93], 0, v[50:51]
	v_pk_mul_f32 v[34:35], v[34:35], v[214:215] op_sel_hi:[1,0]
	v_cvt_pk_bf16_f32 v43, v48, v49
	v_cvt_pk_bf16_f32 v44, v54, v55
	v_cvt_pk_bf16_f32 v45, v56, v57
	v_lshl_add_u64 v[46:47], v[46:47], 0, v[122:123]
	v_pk_mul_f32 v[40:41], v[40:41], v[214:215] op_sel_hi:[1,0]
	v_pk_mul_f32 v[38:39], v[38:39], v[214:215] op_sel_hi:[1,0]
	v_pk_mul_f32 v[36:37], v[36:37], v[214:215] op_sel_hi:[1,0]
	v_max_f32_e32 v34, 0, v34
	v_max_f32_e32 v35, 0, v35
	global_store_dwordx4 v[46:47], v[42:45], off
	v_max_f32_e32 v38, 0, v38
	v_max_f32_e32 v39, 0, v39
	v_pk_mul_f32 v[42:43], v[34:35], v[34:35]
	v_max_f32_e32 v34, 0, v40
	v_max_f32_e32 v36, 0, v36
	v_max_f32_e32 v35, 0, v41
	v_max_f32_e32 v37, 0, v37
	v_pk_mul_f32 v[38:39], v[38:39], v[38:39]
	v_pk_mul_f32 v[40:41], v[34:35], v[34:35]
	v_pk_mul_f32 v[44:45], v[36:37], v[36:37]
	v_cvt_pk_bf16_f32 v34, v38, v39
	v_cvt_pk_bf16_f32 v35, v40, v41
	v_cvt_pk_bf16_f32 v36, v42, v43
	v_cvt_pk_bf16_f32 v37, v44, v45
	global_store_dwordx4 v[46:47], v[34:37], off offset:256
	s_nop 1
	v_add_u32_e32 v34, 0xa0, v158
	v_ashrrev_i32_e32 v35, 31, v34
	v_lshlrev_b64 v[36:37], 7, v[34:35]
	v_lshl_add_u64 v[36:37], v[152:153], 0, v[36:37]
	v_lshlrev_b64 v[34:35], 14, v[34:35]
	v_pk_mul_f32 v[30:31], v[30:31], v[216:217] op_sel_hi:[1,0]
	v_pk_mul_f32 v[26:27], v[26:27], v[216:217] op_sel_hi:[1,0]
	v_pk_mul_f32 v[32:33], v[32:33], v[216:217] op_sel_hi:[1,0]
	v_pk_mul_f32 v[28:29], v[28:29], v[216:217] op_sel_hi:[1,0]
	v_max_f32_e32 v30, 0, v30
	v_max_f32_e32 v26, 0, v26
	v_max_f32_e32 v31, 0, v31
	v_max_f32_e32 v27, 0, v27
	v_pk_mul_f32 v[30:31], v[30:31], v[30:31]
	v_pk_mul_f32 v[38:39], v[26:27], v[26:27]
	v_max_f32_e32 v26, 0, v32
	v_max_f32_e32 v28, 0, v28
	v_max_f32_e32 v27, 0, v33
	v_max_f32_e32 v29, 0, v29
	v_pk_mul_f32 v[32:33], v[26:27], v[26:27]
	v_pk_mul_f32 v[40:41], v[28:29], v[28:29]
	v_cvt_pk_bf16_f32 v26, v30, v31
	v_lshl_add_u64 v[30:31], s[92:93], 0, v[34:35]
	v_pk_mul_f32 v[18:19], v[18:19], v[216:217] op_sel_hi:[1,0]
	v_cvt_pk_bf16_f32 v27, v32, v33
	v_cvt_pk_bf16_f32 v28, v38, v39
	v_cvt_pk_bf16_f32 v29, v40, v41
	v_lshl_add_u64 v[30:31], v[30:31], 0, v[122:123]
	v_pk_mul_f32 v[24:25], v[24:25], v[216:217] op_sel_hi:[1,0]
	v_pk_mul_f32 v[22:23], v[22:23], v[216:217] op_sel_hi:[1,0]
	v_pk_mul_f32 v[20:21], v[20:21], v[216:217] op_sel_hi:[1,0]
	v_max_f32_e32 v18, 0, v18
	v_max_f32_e32 v19, 0, v19
	global_store_dwordx4 v[30:31], v[26:29], off
	v_max_f32_e32 v22, 0, v22
	v_max_f32_e32 v23, 0, v23
	v_pk_mul_f32 v[26:27], v[18:19], v[18:19]
	v_max_f32_e32 v18, 0, v24
	v_max_f32_e32 v20, 0, v20
	v_max_f32_e32 v19, 0, v25
	v_max_f32_e32 v21, 0, v21
	v_pk_mul_f32 v[22:23], v[22:23], v[22:23]
	v_pk_mul_f32 v[24:25], v[18:19], v[18:19]
	v_pk_mul_f32 v[28:29], v[20:21], v[20:21]
	v_cvt_pk_bf16_f32 v18, v22, v23
	v_cvt_pk_bf16_f32 v19, v24, v25
	v_cvt_pk_bf16_f32 v20, v26, v27
	v_cvt_pk_bf16_f32 v21, v28, v29
	global_store_dwordx4 v[30:31], v[18:21], off offset:256
	s_nop 1
	v_add_u32_e32 v18, 0xb0, v158
	v_ashrrev_i32_e32 v19, 31, v18
	v_lshlrev_b64 v[20:21], 7, v[18:19]
	v_lshl_add_u64 v[20:21], v[152:153], 0, v[20:21]
	v_lshlrev_b64 v[18:19], 14, v[18:19]
	s_mov_b64 s[0:1], -1
	v_pk_mul_f32 v[14:15], v[14:15], v[218:219] op_sel_hi:[1,0]
	v_pk_mul_f32 v[10:11], v[10:11], v[218:219] op_sel_hi:[1,0]
	v_pk_mul_f32 v[16:17], v[16:17], v[218:219] op_sel_hi:[1,0]
	v_pk_mul_f32 v[12:13], v[12:13], v[218:219] op_sel_hi:[1,0]
	v_max_f32_e32 v14, 0, v14
	v_max_f32_e32 v10, 0, v10
	v_max_f32_e32 v15, 0, v15
	v_max_f32_e32 v11, 0, v11
	v_pk_mul_f32 v[14:15], v[14:15], v[14:15]
	v_pk_mul_f32 v[22:23], v[10:11], v[10:11]
	v_max_f32_e32 v10, 0, v16
	v_max_f32_e32 v12, 0, v12
	v_max_f32_e32 v11, 0, v17
	v_max_f32_e32 v13, 0, v13
	v_pk_mul_f32 v[16:17], v[10:11], v[10:11]
	v_pk_mul_f32 v[24:25], v[12:13], v[12:13]
	v_cvt_pk_bf16_f32 v10, v14, v15
	v_lshl_add_u64 v[14:15], s[92:93], 0, v[18:19]
	v_pk_mul_f32 v[2:3], v[2:3], v[218:219] op_sel_hi:[1,0]
	v_cvt_pk_bf16_f32 v11, v16, v17
	v_cvt_pk_bf16_f32 v12, v22, v23
	v_cvt_pk_bf16_f32 v13, v24, v25
	v_lshl_add_u64 v[14:15], v[14:15], 0, v[122:123]
	v_pk_mul_f32 v[8:9], v[8:9], v[218:219] op_sel_hi:[1,0]
	v_pk_mul_f32 v[6:7], v[6:7], v[218:219] op_sel_hi:[1,0]
	v_pk_mul_f32 v[4:5], v[4:5], v[218:219] op_sel_hi:[1,0]
	v_max_f32_e32 v2, 0, v2
	v_max_f32_e32 v3, 0, v3
	global_store_dwordx4 v[14:15], v[10:13], off
	v_max_f32_e32 v6, 0, v6
	v_max_f32_e32 v7, 0, v7
	v_pk_mul_f32 v[10:11], v[2:3], v[2:3]
	v_max_f32_e32 v2, 0, v8
	v_max_f32_e32 v4, 0, v4
	v_max_f32_e32 v3, 0, v9
	v_max_f32_e32 v5, 0, v5
	v_pk_mul_f32 v[6:7], v[6:7], v[6:7]
	v_pk_mul_f32 v[8:9], v[2:3], v[2:3]
	v_pk_mul_f32 v[12:13], v[4:5], v[4:5]
	v_cvt_pk_bf16_f32 v2, v6, v7
	v_cvt_pk_bf16_f32 v3, v8, v9
	v_cvt_pk_bf16_f32 v4, v10, v11
	v_cvt_pk_bf16_f32 v5, v12, v13
	s_andn2_b64 vcc, exec, s[40:41]
	global_store_dwordx4 v[14:15], v[2:5], off offset:256
	s_cbranch_vccnz .LBB0_68
	s_andn2_b64 vcc, exec, s[12:13]
	s_cbranch_vccnz .LBB0_67
	s_barrier
	s_branch .LBB0_67
